# dots: removed artifact vmcnt ladders/copies in token loop (single wait at loop entry)
# speedup vs baseline: 1.0301x; 1.0044x over previous
; DI void expert_dots(const Params& p, int nrows, char* smem) {
;     ...
;   const int tstep = wpx * 4;
;   int t = jx * 4 + wave;
;   int ni0 = 0, ni1 = 0;
;   uint4 nh[8];
;   auto prefetch = [&](int tt) {
;     { const u32 w2 = ((const u32*)IDX)[(size_t)tt * 64 + lane]; ni0 = (int)(w2 & 0xffffu); ni1 = (int)(w2 >> 16); }
; #pragma unroll
;     for (int c = 0; c < 4; c++) {
;       const u16* hp = p.H + (size_t)tt * D + (c * 16 + s) * 16;
;       nh[2 * c] = *(const uint4*)(hp); nh[2 * c + 1] = *(const uint4*)(hp + 8);
;     }
;   };
;   auto dot_row = [&](const int4 (&uu)[4], const f2 (&hf)[32]) {
;     const int uw[16] = {uu[0].x, uu[0].y, uu[0].z, uu[0].w, uu[1].x, uu[1].y, uu[1].z, uu[1].w,
;                         uu[2].x, uu[2].y, uu[2].z, uu[2].w, uu[3].x, uu[3].y, uu[3].z, uu[3].w};
;     f2 acc = {0.f, 0.f}, acc2 = {0.f, 0.f};
; #pragma unroll
;     for (int j = 0; j < 16; j++) {
;       acc = __builtin_elementwise_fma(__builtin_amdgcn_cvt_pk_f32_fp8(uw[j], false), hf[2 * j], acc);
;       acc2 = __builtin_elementwise_fma(__builtin_amdgcn_cvt_pk_f32_fp8(uw[j], true), hf[2 * j + 1], acc2);
;     }
;     return row16_sum((acc.x + acc.y) + (acc2.x + acc2.y));
;   };
;   if (t < nrows) prefetch(t);
;   for (; t < nrows; t += tstep) {
;     const int i0 = ni0, i1 = ni1;
;     f2 hf[32];
; #pragma unroll
;     for (int c = 0; c < 4; c++) {
;       const u32 hw[8] = {nh[2 * c].x, nh[2 * c].y, nh[2 * c].z, nh[2 * c].w, nh[2 * c + 1].x, nh[2 * c + 1].y, nh[2 * c + 1].z, nh[2 * c + 1].w};
; #pragma unroll
;       for (int j = 0; j < 8; j++) { hf[c * 8 + j].x = __uint_as_float(hw[j] << 16); hf[c * 8 + j].y = __uint_as_float(hw[j] & 0xffff0000u); }
;     }
;     if (t + tstep < nrows) prefetch(t + tstep);
.LBB0_1071:
	s_andn2_b64 vcc, exec, s[0:1]
	s_cbranch_vccnz .LBB0_1142
	s_waitcnt vmcnt(3) lgkmcnt(0)
	v_mov_b32_e32 v1, v220
	s_mov_b32 s0, s74
	s_ashr_i32 s1, s0, 1
	v_ashrrev_i32_e32 v0, 6, v1
	s_and_b32 s1, s1, -4
	v_add_u32_e32 v104, s1, v0
	v_cmp_gt_i32_e32 vcc, s54, v104
	s_and_saveexec_b64 s[40:41], vcc
	s_cbranch_execz .LBB0_1088
	s_and_b32 s24, s0, 7
	v_readlane_b32 s0, v252, 36
	s_sub_i32 s0, s0, s24
	s_lshr_b32 s0, s0, 1
	v_and_b32_e32 v107, 15, v1
	s_and_b32 s36, s0, 0x7ffffffc
	v_ashrrev_i32_e32 v105, 31, v104
	v_readlane_b32 s0, v251, 37
	s_waitcnt vmcnt(2)
	v_and_b32_e32 v4, 63, v1
	v_bfe_u32 v106, v1, 4, 2
	v_lshlrev_b32_e32 v108, 9, v0
	v_lshlrev_b32_e32 v196, 4, v107
	v_lshlrev_b64 v[0:1], 8, v[104:105]
	v_readlane_b32 s1, v251, 38
	v_lshl_add_u64 v[64:65], s[18:19], 0, v[196:197]
	v_lshlrev_b32_e32 v196, 2, v4
	v_lshl_add_u64 v[0:1], s[0:1], 0, v[0:1]
	v_lshl_add_u64 v[0:1], v[0:1], 0, v[196:197]
	global_load_dword v0, v[0:1], off
	v_lshlrev_b32_e32 v2, 5, v107
	v_mov_b32_e32 v3, v197
	v_lshlrev_b32_e32 v109, 17, v4
	v_lshl_add_u64 v[66:67], s[0:1], 0, v[196:197]
	v_lshl_or_b32 v110, v107, 2, v106
	v_lshl_add_u64 v[68:69], s[10:11], 0, v[2:3]
	v_or_b32_e32 v111, 0x10000, v109
	s_mov_b64 s[42:43], 0
	s_waitcnt vmcnt(0)
	v_and_b32_e32 v73, 0xffff, v0
	v_lshrrev_b32_e32 v72, 16, v0
	v_lshlrev_b64 v[0:1], 11, v[104:105]
	v_lshl_add_u64 v[0:1], s[10:11], 0, v[0:1]
	v_lshl_add_u64 v[0:1], v[0:1], 0, v[2:3]
	global_load_dwordx4 v[32:35], v[0:1], off offset:16
	global_load_dwordx4 v[48:51], v[0:1], off
	global_load_dwordx4 v[36:39], v[0:1], off offset:528
	global_load_dwordx4 v[52:55], v[0:1], off offset:512
	global_load_dwordx4 v[40:43], v[0:1], off offset:1040
	global_load_dwordx4 v[56:59], v[0:1], off offset:1024
	global_load_dwordx4 v[44:47], v[0:1], off offset:1552
	global_load_dwordx4 v[60:63], v[0:1], off offset:1536
	v_mov_b32_e32 v71, v72
	v_mov_b32_e32 v112, v73
	s_waitcnt vmcnt(0)
	s_branch .LBB0_1075
.Ldp_1074a:
	s_and_b64 s[0:1], exec, s[38:39]
	s_or_b64 s[42:43], s[0:1], s[42:43]
	v_mov_b32_e32 v104, v70
	s_waitcnt vmcnt(0)
	s_branch .Ldp_1074j
.LBB0_1074:
	s_and_b64 s[0:1], exec, s[38:39]
	s_or_b64 s[42:43], s[0:1], s[42:43]
	v_mov_b32_e32 v104, v70
	s_waitcnt vmcnt(1)
.Ldp_1074j:
	v_and_b32_e32 v73, 0xffff, v207
	v_lshrrev_b32_e32 v72, 16, v207
	v_mov_b64_e32 v[48:49], v[4:5]
	v_mov_b64_e32 v[50:51], v[6:7]
	v_mov_b64_e32 v[32:33], v[0:1]
	v_mov_b64_e32 v[34:35], v[2:3]
	v_mov_b64_e32 v[52:53], v[12:13]
	v_mov_b64_e32 v[54:55], v[14:15]
	v_mov_b64_e32 v[36:37], v[8:9]
	v_mov_b64_e32 v[38:39], v[10:11]
	v_mov_b64_e32 v[56:57], v[20:21]
	v_mov_b64_e32 v[58:59], v[22:23]
	v_mov_b64_e32 v[40:41], v[16:17]
	v_mov_b64_e32 v[42:43], v[18:19]
	v_mov_b64_e32 v[60:61], v[28:29]
	v_mov_b64_e32 v[62:63], v[30:31]
	v_mov_b64_e32 v[44:45], v[24:25]
	v_mov_b64_e32 v[46:47], v[26:27]
	v_readlane_b32 s33, v250, 15
	s_andn2_b64 exec, exec, s[42:43]
	s_cbranch_execz .LBB0_1088
.LBB0_1075:
	v_add_u32_e32 v70, s36, v104
	v_cmp_gt_i32_e32 vcc, s54, v70
	v_cmp_le_i32_e64 s[38:39], s54, v70
	s_and_saveexec_b64 s[0:1], vcc
	s_cbranch_execz .LBB0_1077
	v_ashrrev_i32_e32 v71, 31, v70
	v_lshlrev_b64 v[0:1], 8, v[70:71]
	v_lshl_add_u64 v[0:1], v[66:67], 0, v[0:1]
	global_load_dword v207, v[0:1], off
	v_lshlrev_b64 v[0:1], 11, v[70:71]
	v_lshl_add_u64 v[28:29], v[68:69], 0, v[0:1]
	global_load_dwordx4 v[0:3], v[28:29], off offset:16
	global_load_dwordx4 v[4:7], v[28:29], off
	global_load_dwordx4 v[8:11], v[28:29], off offset:528
	global_load_dwordx4 v[12:15], v[28:29], off offset:512
	global_load_dwordx4 v[16:19], v[28:29], off offset:1040
	global_load_dwordx4 v[20:23], v[28:29], off offset:1024
	global_load_dwordx4 v[24:27], v[28:29], off offset:1552
	s_nop 0
	global_load_dwordx4 v[28:31], v[28:29], off offset:1536
